# v193 without the PV batch-wait change (batch-3 V reads back after the batch-1 MFMAs, single wait)
# baseline (speedup 1.0000x reference)
.LBB0_1126:
	v_sub_f32_e32 v128, v128, v143
	v_exp_f32_e32 v128, v128
	v_sub_f32_e32 v129, v129, v143
	v_exp_f32_e32 v129, v129
	v_sub_f32_e32 v130, v130, v143
	v_exp_f32_e32 v130, v130
	v_sub_f32_e32 v131, v131, v143
	v_exp_f32_e32 v131, v131
	v_sub_f32_e32 v124, v124, v143
	v_add_f32_e32 v165, 0, v128
	v_exp_f32_e32 v124, v124
	v_sub_f32_e32 v125, v125, v143
	v_add_f32_e32 v165, v129, v165
	v_exp_f32_e32 v125, v125
	v_sub_f32_e32 v126, v126, v143
	v_add_f32_e32 v165, v130, v165
	v_exp_f32_e32 v126, v126
	v_sub_f32_e32 v127, v127, v143
	v_add_f32_e32 v165, v131, v165
	v_exp_f32_e32 v127, v127
	v_sub_f32_e32 v120, v120, v143
	v_add_f32_e32 v165, v124, v165
	v_exp_f32_e32 v166, v120
	v_sub_f32_e32 v120, v121, v143
	v_add_f32_e32 v165, v125, v165
	v_exp_f32_e32 v167, v120
	v_sub_f32_e32 v120, v122, v143
	v_add_f32_e32 v165, v126, v165
	v_exp_f32_e32 v168, v120
	v_sub_f32_e32 v120, v123, v143
	v_add_f32_e32 v165, v127, v165
	v_exp_f32_e32 v123, v120
	v_sub_f32_e32 v116, v116, v143
	v_add_f32_e32 v120, v166, v165
	v_exp_f32_e32 v165, v116
	v_sub_f32_e32 v116, v117, v143
	v_add_f32_e32 v120, v167, v120
	v_exp_f32_e32 v117, v116
	v_sub_f32_e32 v116, v118, v143
	v_add_f32_e32 v120, v168, v120
	v_exp_f32_e32 v169, v116
	v_sub_f32_e32 v116, v119, v143
	v_add_f32_e32 v120, v123, v120
	v_exp_f32_e32 v170, v116
	v_add_f32_e32 v116, v165, v120
	v_add_f32_e32 v116, v117, v116
	v_add_f32_e32 v116, v169, v116
	v_add_f32_e32 v116, v170, v116
	v_fmac_f32_e32 v116, v1, v2
	v_cvt_pk_bf16_f32 v118, v128, v129
	v_cvt_pk_bf16_f32 v119, v130, v131
	v_cvt_pk_bf16_f32 v120, v124, v125
	v_cvt_pk_bf16_f32 v121, v126, v127
	v_cvt_pk_bf16_f32 v122, v166, v167
	v_cvt_pk_bf16_f32 v123, v168, v123
	v_cvt_pk_bf16_f32 v124, v165, v117
	v_cvt_pk_bf16_f32 v125, v169, v170
	s_waitcnt lgkmcnt(0)
	v_mfma_f32_16x16x32_bf16 v[80:83], v[100:103], v[118:121], v[80:83]
	v_mfma_f32_16x16x32_bf16 v[76:79], v[88:91], v[118:121], v[76:79]
	v_mfma_f32_16x16x32_bf16 v[72:75], v[92:95], v[118:121], v[72:75]
	v_mfma_f32_16x16x32_bf16 v[68:71], v[84:87], v[118:121], v[68:71]
	v_mfma_f32_16x16x32_bf16 v[80:83], v[112:115], v[122:125], v[80:83]
	v_mfma_f32_16x16x32_bf16 v[76:79], v[104:107], v[122:125], v[76:79]
	v_mfma_f32_16x16x32_bf16 v[72:75], v[108:111], v[122:125], v[72:75]
	v_mfma_f32_16x16x32_bf16 v[68:71], v[96:99], v[122:125], v[68:71]
	ds_read_b128 v[84:87], v3 offset:16384
	ds_read_b128 v[88:91], v3 offset:18432
	ds_read_b128 v[92:95], v145 offset:16384
	ds_read_b128 v[96:99], v145 offset:18432
	ds_read_b128 v[100:103], v3 offset:20480
	ds_read_b128 v[104:107], v3 offset:22528
	ds_read_b128 v[108:111], v145 offset:20480
	ds_read_b128 v[112:115], v145 offset:22528
	v_mfma_f32_16x16x32_bf16 v[64:67], v[194:197], v[118:121], v[64:67]
	v_mfma_f32_16x16x32_bf16 v[60:63], v[198:201], v[118:121], v[60:63]
	v_mfma_f32_16x16x32_bf16 v[56:59], v[210:213], v[118:121], v[56:59]
	v_mfma_f32_16x16x32_bf16 v[52:55], v[214:217], v[118:121], v[52:55]
	v_mfma_f32_16x16x32_bf16 v[64:67], v[202:205], v[122:125], v[64:67]
	v_mfma_f32_16x16x32_bf16 v[60:63], v[206:209], v[122:125], v[60:63]
	v_mfma_f32_16x16x32_bf16 v[56:59], v[218:221], v[122:125], v[56:59]
	v_mfma_f32_16x16x32_bf16 v[52:55], v[222:225], v[122:125], v[52:55]
	ds_read_b128 v[126:129], v3 offset:24576
	ds_read_b128 v[166:169], v3 offset:26624
	ds_read_b128 v[170:173], v145 offset:24576
	ds_read_b128 v[174:177], v145 offset:26624
	ds_read_b128 v[178:181], v3 offset:28672
	ds_read_b128 v[182:185], v3 offset:30720
	ds_read_b128 v[186:189], v145 offset:28672
	ds_read_b128 v[190:193], v145 offset:30720
	s_waitcnt lgkmcnt(0)
	v_mfma_f32_16x16x32_bf16 v[48:51], v[84:87], v[118:121], v[48:51]
	v_mfma_f32_16x16x32_bf16 v[44:47], v[88:91], v[118:121], v[44:47]
	v_mfma_f32_16x16x32_bf16 v[40:43], v[100:103], v[118:121], v[40:43]
	v_mfma_f32_16x16x32_bf16 v[36:39], v[104:107], v[118:121], v[36:39]
	v_mfma_f32_16x16x32_bf16 v[48:51], v[92:95], v[122:125], v[48:51]
	v_mfma_f32_16x16x32_bf16 v[44:47], v[96:99], v[122:125], v[44:47]
	v_mfma_f32_16x16x32_bf16 v[40:43], v[108:111], v[122:125], v[40:43]
	v_mfma_f32_16x16x32_bf16 v[36:39], v[112:115], v[122:125], v[36:39]
	v_mfma_f32_16x16x32_bf16 v[32:35], v[126:129], v[118:121], v[32:35]
	v_mfma_f32_16x16x32_bf16 v[28:31], v[166:169], v[118:121], v[28:31]
	v_mfma_f32_16x16x32_bf16 v[24:27], v[178:181], v[118:121], v[24:27]
	v_mfma_f32_16x16x32_bf16 v[20:23], v[182:185], v[118:121], v[20:23]
	v_mfma_f32_16x16x32_bf16 v[32:35], v[170:173], v[122:125], v[32:35]
	v_mfma_f32_16x16x32_bf16 v[28:31], v[174:177], v[122:125], v[28:31]
	v_mfma_f32_16x16x32_bf16 v[24:27], v[186:189], v[122:125], v[24:27]
	v_mfma_f32_16x16x32_bf16 v[20:23], v[190:193], v[122:125], v[20:23]
	s_add_i32 s50, s50, 64
	s_cmp_eq_u32 s69, s70
	s_cbranch_scc1 .LBB0_1129
	v_mov_b32_e32 v1, v116
	s_branch .LBB0_1117
